# P0a adaLN GEMV row loop: rolling refill keeps 8 row loads in flight per wave (saddr-form loads, scalar row pointer) on top of cvstore/sinkfix/noflush stack
# baseline (speedup 1.0000x reference)
.LBB0_52:
	v_and_b32_e32 v5, 0x1800, v2
	v_add_u32_e32 v4, 64, v4
	v_add_u32_e32 v5, s27, v5
	v_and_or_b32 v6, v4, s30, v5
	v_ashrrev_i32_e32 v7, 31, v6
	v_lshl_add_u64 v[6:7], v[6:7], 2, s[16:17]
	global_load_dword v5, v[6:7], off
	v_cmp_lt_u32_e32 vcc, s31, v4
	s_or_b64 s[18:19], vcc, s[18:19]
	v_add_u32_e32 v2, 0x200, v2
	s_waitcnt vmcnt(0)
	v_mul_f32_e32 v6, 0xbfb8aa3b, v5
	v_exp_f32_e32 v6, v6
	s_nop 0
	v_add_f32_e32 v6, 1.0, v6
	v_div_scale_f32 v7, s[4:5], v6, v6, v5
	v_rcp_f32_e32 v8, v7
	v_div_scale_f32 v9, vcc, v5, v6, v5
	v_fma_f32 v10, -v7, v8, 1.0
	v_fmac_f32_e32 v8, v10, v8
	v_mul_f32_e32 v10, v9, v8
	v_fma_f32 v11, -v7, v10, v9
	v_fmac_f32_e32 v10, v11, v8
	v_fma_f32 v7, -v7, v10, v9
	v_div_fmas_f32 v7, v7, v8, v10
	v_div_fixup_f32 v5, v7, v6, v5
	ds_write_b32 v3, v5
	v_add_u32_e32 v3, 0x100, v3
	s_andn2_b64 exec, exec, s[18:19]
	s_cbranch_execnz .LBB0_52
	s_or_b64 exec, exec, s[18:19]
	s_ashr_i32 s4, s20, 3
	s_mul_hi_i32 s5, s4, 0x2aaaaaab
	s_lshr_b32 s6, s5, 31
	s_lshr_b32 s5, s5, 3
	s_add_i32 s5, s5, s6
	s_mul_i32 s5, s5, 48
	s_sub_i32 s8, s4, s5
	s_mul_hi_i32 s4, s20, 0x2aaaaaab
	s_lshr_b32 s5, s4, 31
	s_ashr_i32 s4, s4, 6
	s_add_i32 s4, s4, s5
	s_ashr_i32 s5, s4, 31
	s_lshl_b64 s[6:7], s[4:5], 11
	s_or_b32 s5, s6, s26
	s_mul_i32 s6, s7, 0xc000
	s_mul_hi_u32 s7, s5, 0xc000
	s_add_i32 s7, s7, s6
	s_mul_i32 s5, s5, 0xc000
	s_add_u32 s5, s14, s5
	s_addc_u32 s9, s15, s7
	s_lshl_b32 s6, s8, 8
	s_ashr_i32 s7, s6, 31
	s_waitcnt lgkmcnt(0)
	s_lshl_b64 s[6:7], s[6:7], 2
	s_add_u32 s8, s5, s6
	s_addc_u32 s9, s9, s7
	s_mov_b64 s[98:99], s[8:9]
	v_lshlrev_b32_e32 v16, 2, v14
	v_mov_b32_e32 v6, 0
	v_lshl_add_u64 v[22:23], s[8:9], 0, v[16:17]
	s_mov_b64 s[8:9], 0
	s_mov_b32 s5, s22
	v_mov_b32_e32 v7, v6
	v_mov_b32_e32 v8, v6
	v_mov_b32_e32 v9, v6
	v_mov_b32_e32 v10, v6
	v_mov_b32_e32 v11, v6
	v_mov_b32_e32 v12, v6
	v_mov_b32_e32 v13, v6
	v_mov_b32_e32 v2, v6
	v_mov_b32_e32 v3, v6
	v_mov_b32_e32 v4, v6
	v_mov_b32_e32 v5, v6
.LBB0_54:
	s_mov_b64 s[100:101], s[98:99]
	global_load_dwordx4 v[52:55], v16, s[100:101] nt
	s_add_u32 s100, s100, 0xc000
	s_addc_u32 s101, s101, 0
	global_load_dwordx4 v[56:59], v16, s[100:101] nt
	s_add_u32 s100, s100, 0xc000
	s_addc_u32 s101, s101, 0
	global_load_dwordx4 v[60:63], v16, s[100:101] nt
	s_add_u32 s100, s100, 0xc000
	s_addc_u32 s101, s101, 0
	global_load_dwordx4 v[64:67], v16, s[100:101] nt
	s_add_u32 s100, s100, 0xc000
	s_addc_u32 s101, s101, 0
	global_load_dwordx4 v[68:71], v16, s[100:101] nt
	s_add_u32 s100, s100, 0xc000
	s_addc_u32 s101, s101, 0
	global_load_dwordx4 v[72:75], v16, s[100:101] nt
	s_add_u32 s100, s100, 0xc000
	s_addc_u32 s101, s101, 0
	global_load_dwordx4 v[76:79], v16, s[100:101] nt
	s_add_u32 s100, s100, 0xc000
	s_addc_u32 s101, s101, 0
	global_load_dwordx4 v[80:83], v16, s[100:101] nt
	s_add_u32 s100, s100, 0xc000
	s_addc_u32 s101, s101, 0
.Lgv_loop:
	v_mov_b32_e32 v19, s5
	ds_read_b128 v[84:87], v19
	ds_read_b128 v[88:91], v19 offset:16
	ds_read_b128 v[92:95], v19 offset:1024
	ds_read_b128 v[96:99], v19 offset:1040
	ds_read_b128 v[100:103], v19 offset:2048
	ds_read_b128 v[104:107], v19 offset:2064
	s_waitcnt lgkmcnt(5)
	v_mov_b32_e32 v108, v87
	s_waitcnt lgkmcnt(3)
	v_mov_b32_e32 v110, v95
	v_mov_b32_e32 v114, v91
	s_waitcnt lgkmcnt(1)
	v_mov_b32_e32 v112, v103
	v_mov_b32_e32 v116, v99
	s_waitcnt lgkmcnt(0)
	v_mov_b32_e32 v118, v107
	s_add_i32 s5, s5, 32
	s_add_u32 s8, s8, 0x60000
	s_addc_u32 s9, s9, 0
	s_cmp_lg_u32 s8, 0xc00000
	s_cbranch_scc0 .Lgv_last
	s_waitcnt vmcnt(7)
	v_pk_fma_f32 v[8:9], v[54:55], v[84:85], v[8:9] op_sel_hi:[1,0,1]
	v_pk_fma_f32 v[6:7], v[52:53], v[84:85], v[6:7] op_sel_hi:[1,0,1]
	v_pk_fma_f32 v[12:13], v[54:55], v[92:93], v[12:13] op_sel_hi:[1,0,1]
	v_pk_fma_f32 v[10:11], v[52:53], v[92:93], v[10:11] op_sel_hi:[1,0,1]
	v_pk_fma_f32 v[4:5], v[54:55], v[100:101], v[4:5] op_sel_hi:[1,0,1]
	v_pk_fma_f32 v[2:3], v[52:53], v[100:101], v[2:3] op_sel_hi:[1,0,1]
	global_load_dwordx4 v[52:55], v16, s[100:101] nt
	s_add_u32 s100, s100, 0xc000
	s_addc_u32 s101, s101, 0
	s_waitcnt vmcnt(7)
	v_pk_fma_f32 v[6:7], v[56:57], v[84:85], v[6:7] op_sel:[0,1,0]
	v_pk_fma_f32 v[8:9], v[58:59], v[84:85], v[8:9] op_sel:[0,1,0]
	v_pk_fma_f32 v[10:11], v[56:57], v[92:93], v[10:11] op_sel:[0,1,0]
	v_pk_fma_f32 v[12:13], v[58:59], v[92:93], v[12:13] op_sel:[0,1,0]
	v_pk_fma_f32 v[2:3], v[56:57], v[100:101], v[2:3] op_sel:[0,1,0]
	v_pk_fma_f32 v[4:5], v[58:59], v[100:101], v[4:5] op_sel:[0,1,0]
	global_load_dwordx4 v[56:59], v16, s[100:101] nt
	s_add_u32 s100, s100, 0xc000
	s_addc_u32 s101, s101, 0
	s_waitcnt vmcnt(7)
	v_pk_fma_f32 v[8:9], v[62:63], v[86:87], v[8:9] op_sel_hi:[1,0,1]
	v_pk_fma_f32 v[6:7], v[60:61], v[86:87], v[6:7] op_sel_hi:[1,0,1]
	v_pk_fma_f32 v[12:13], v[62:63], v[94:95], v[12:13] op_sel_hi:[1,0,1]
	v_pk_fma_f32 v[10:11], v[60:61], v[94:95], v[10:11] op_sel_hi:[1,0,1]
	v_pk_fma_f32 v[4:5], v[62:63], v[102:103], v[4:5] op_sel_hi:[1,0,1]
	v_pk_fma_f32 v[2:3], v[60:61], v[102:103], v[2:3] op_sel_hi:[1,0,1]
	global_load_dwordx4 v[60:63], v16, s[100:101] nt
	s_add_u32 s100, s100, 0xc000
	s_addc_u32 s101, s101, 0
	s_waitcnt vmcnt(7)
	v_pk_fma_f32 v[8:9], v[66:67], v[108:109], v[8:9] op_sel_hi:[1,0,1]
	v_pk_fma_f32 v[6:7], v[64:65], v[108:109], v[6:7] op_sel_hi:[1,0,1]
	v_pk_fma_f32 v[12:13], v[66:67], v[110:111], v[12:13] op_sel_hi:[1,0,1]
	v_pk_fma_f32 v[10:11], v[64:65], v[110:111], v[10:11] op_sel_hi:[1,0,1]
	v_pk_fma_f32 v[4:5], v[66:67], v[112:113], v[4:5] op_sel_hi:[1,0,1]
	v_pk_fma_f32 v[2:3], v[64:65], v[112:113], v[2:3] op_sel_hi:[1,0,1]
	global_load_dwordx4 v[64:67], v16, s[100:101] nt
	s_add_u32 s100, s100, 0xc000
	s_addc_u32 s101, s101, 0
	s_waitcnt vmcnt(7)
	v_pk_fma_f32 v[8:9], v[70:71], v[88:89], v[8:9] op_sel_hi:[1,0,1]
	v_pk_fma_f32 v[6:7], v[68:69], v[88:89], v[6:7] op_sel_hi:[1,0,1]
	v_pk_fma_f32 v[12:13], v[70:71], v[96:97], v[12:13] op_sel_hi:[1,0,1]
	v_pk_fma_f32 v[10:11], v[68:69], v[96:97], v[10:11] op_sel_hi:[1,0,1]
	v_pk_fma_f32 v[4:5], v[70:71], v[104:105], v[4:5] op_sel_hi:[1,0,1]
	v_pk_fma_f32 v[2:3], v[68:69], v[104:105], v[2:3] op_sel_hi:[1,0,1]
	global_load_dwordx4 v[68:71], v16, s[100:101] nt
	s_add_u32 s100, s100, 0xc000
	s_addc_u32 s101, s101, 0
	s_waitcnt vmcnt(7)
	v_pk_fma_f32 v[8:9], v[74:75], v[88:89], v[8:9] op_sel:[0,1,0]
	v_pk_fma_f32 v[6:7], v[72:73], v[88:89], v[6:7] op_sel:[0,1,0]
	v_pk_fma_f32 v[12:13], v[74:75], v[96:97], v[12:13] op_sel:[0,1,0]
	v_pk_fma_f32 v[10:11], v[72:73], v[96:97], v[10:11] op_sel:[0,1,0]
	v_pk_fma_f32 v[4:5], v[74:75], v[104:105], v[4:5] op_sel:[0,1,0]
	v_pk_fma_f32 v[2:3], v[72:73], v[104:105], v[2:3] op_sel:[0,1,0]
	global_load_dwordx4 v[72:75], v16, s[100:101] nt
	s_add_u32 s100, s100, 0xc000
	s_addc_u32 s101, s101, 0
	s_waitcnt vmcnt(7)
	v_pk_fma_f32 v[8:9], v[78:79], v[90:91], v[8:9] op_sel_hi:[1,0,1]
	v_pk_fma_f32 v[6:7], v[76:77], v[90:91], v[6:7] op_sel_hi:[1,0,1]
	v_pk_fma_f32 v[12:13], v[78:79], v[98:99], v[12:13] op_sel_hi:[1,0,1]
	v_pk_fma_f32 v[10:11], v[76:77], v[98:99], v[10:11] op_sel_hi:[1,0,1]
	v_pk_fma_f32 v[4:5], v[78:79], v[106:107], v[4:5] op_sel_hi:[1,0,1]
	v_pk_fma_f32 v[2:3], v[76:77], v[106:107], v[2:3] op_sel_hi:[1,0,1]
	global_load_dwordx4 v[76:79], v16, s[100:101] nt
	s_add_u32 s100, s100, 0xc000
	s_addc_u32 s101, s101, 0
	s_waitcnt vmcnt(7)
	v_pk_fma_f32 v[8:9], v[82:83], v[114:115], v[8:9] op_sel_hi:[1,0,1]
	v_pk_fma_f32 v[6:7], v[80:81], v[114:115], v[6:7] op_sel_hi:[1,0,1]
	v_pk_fma_f32 v[12:13], v[82:83], v[116:117], v[12:13] op_sel_hi:[1,0,1]
	v_pk_fma_f32 v[10:11], v[80:81], v[116:117], v[10:11] op_sel_hi:[1,0,1]
	v_pk_fma_f32 v[4:5], v[82:83], v[118:119], v[4:5] op_sel_hi:[1,0,1]
	v_pk_fma_f32 v[2:3], v[80:81], v[118:119], v[2:3] op_sel_hi:[1,0,1]
	global_load_dwordx4 v[80:83], v16, s[100:101] nt
	s_add_u32 s100, s100, 0xc000
	s_addc_u32 s101, s101, 0
	s_branch .Lgv_loop
.Lgv_last:
	s_waitcnt vmcnt(7)
	v_pk_fma_f32 v[8:9], v[54:55], v[84:85], v[8:9] op_sel_hi:[1,0,1]
	v_pk_fma_f32 v[6:7], v[52:53], v[84:85], v[6:7] op_sel_hi:[1,0,1]
	v_pk_fma_f32 v[12:13], v[54:55], v[92:93], v[12:13] op_sel_hi:[1,0,1]
	v_pk_fma_f32 v[10:11], v[52:53], v[92:93], v[10:11] op_sel_hi:[1,0,1]
	v_pk_fma_f32 v[4:5], v[54:55], v[100:101], v[4:5] op_sel_hi:[1,0,1]
	v_pk_fma_f32 v[2:3], v[52:53], v[100:101], v[2:3] op_sel_hi:[1,0,1]
	s_waitcnt vmcnt(6)
	v_pk_fma_f32 v[6:7], v[56:57], v[84:85], v[6:7] op_sel:[0,1,0]
	v_pk_fma_f32 v[8:9], v[58:59], v[84:85], v[8:9] op_sel:[0,1,0]
	v_pk_fma_f32 v[10:11], v[56:57], v[92:93], v[10:11] op_sel:[0,1,0]
	v_pk_fma_f32 v[12:13], v[58:59], v[92:93], v[12:13] op_sel:[0,1,0]
	v_pk_fma_f32 v[2:3], v[56:57], v[100:101], v[2:3] op_sel:[0,1,0]
	v_pk_fma_f32 v[4:5], v[58:59], v[100:101], v[4:5] op_sel:[0,1,0]
	s_waitcnt vmcnt(5)
	v_pk_fma_f32 v[8:9], v[62:63], v[86:87], v[8:9] op_sel_hi:[1,0,1]
	v_pk_fma_f32 v[6:7], v[60:61], v[86:87], v[6:7] op_sel_hi:[1,0,1]
	v_pk_fma_f32 v[12:13], v[62:63], v[94:95], v[12:13] op_sel_hi:[1,0,1]
	v_pk_fma_f32 v[10:11], v[60:61], v[94:95], v[10:11] op_sel_hi:[1,0,1]
	v_pk_fma_f32 v[4:5], v[62:63], v[102:103], v[4:5] op_sel_hi:[1,0,1]
	v_pk_fma_f32 v[2:3], v[60:61], v[102:103], v[2:3] op_sel_hi:[1,0,1]
	s_waitcnt vmcnt(4)
	v_pk_fma_f32 v[8:9], v[66:67], v[108:109], v[8:9] op_sel_hi:[1,0,1]
	v_pk_fma_f32 v[6:7], v[64:65], v[108:109], v[6:7] op_sel_hi:[1,0,1]
	v_pk_fma_f32 v[12:13], v[66:67], v[110:111], v[12:13] op_sel_hi:[1,0,1]
	v_pk_fma_f32 v[10:11], v[64:65], v[110:111], v[10:11] op_sel_hi:[1,0,1]
	v_pk_fma_f32 v[4:5], v[66:67], v[112:113], v[4:5] op_sel_hi:[1,0,1]
	v_pk_fma_f32 v[2:3], v[64:65], v[112:113], v[2:3] op_sel_hi:[1,0,1]
	s_waitcnt vmcnt(3)
	v_pk_fma_f32 v[8:9], v[70:71], v[88:89], v[8:9] op_sel_hi:[1,0,1]
	v_pk_fma_f32 v[6:7], v[68:69], v[88:89], v[6:7] op_sel_hi:[1,0,1]
	v_pk_fma_f32 v[12:13], v[70:71], v[96:97], v[12:13] op_sel_hi:[1,0,1]
	v_pk_fma_f32 v[10:11], v[68:69], v[96:97], v[10:11] op_sel_hi:[1,0,1]
	v_pk_fma_f32 v[4:5], v[70:71], v[104:105], v[4:5] op_sel_hi:[1,0,1]
	v_pk_fma_f32 v[2:3], v[68:69], v[104:105], v[2:3] op_sel_hi:[1,0,1]
	s_waitcnt vmcnt(2)
	v_pk_fma_f32 v[8:9], v[74:75], v[88:89], v[8:9] op_sel:[0,1,0]
	v_pk_fma_f32 v[6:7], v[72:73], v[88:89], v[6:7] op_sel:[0,1,0]
	v_pk_fma_f32 v[12:13], v[74:75], v[96:97], v[12:13] op_sel:[0,1,0]
	v_pk_fma_f32 v[10:11], v[72:73], v[96:97], v[10:11] op_sel:[0,1,0]
	v_pk_fma_f32 v[4:5], v[74:75], v[104:105], v[4:5] op_sel:[0,1,0]
	v_pk_fma_f32 v[2:3], v[72:73], v[104:105], v[2:3] op_sel:[0,1,0]
	s_waitcnt vmcnt(1)
	v_pk_fma_f32 v[8:9], v[78:79], v[90:91], v[8:9] op_sel_hi:[1,0,1]
	v_pk_fma_f32 v[6:7], v[76:77], v[90:91], v[6:7] op_sel_hi:[1,0,1]
	v_pk_fma_f32 v[12:13], v[78:79], v[98:99], v[12:13] op_sel_hi:[1,0,1]
	v_pk_fma_f32 v[10:11], v[76:77], v[98:99], v[10:11] op_sel_hi:[1,0,1]
	v_pk_fma_f32 v[4:5], v[78:79], v[106:107], v[4:5] op_sel_hi:[1,0,1]
	v_pk_fma_f32 v[2:3], v[76:77], v[106:107], v[2:3] op_sel_hi:[1,0,1]
	s_waitcnt vmcnt(0)
	v_pk_fma_f32 v[8:9], v[82:83], v[114:115], v[8:9] op_sel_hi:[1,0,1]
	v_pk_fma_f32 v[6:7], v[80:81], v[114:115], v[6:7] op_sel_hi:[1,0,1]
	v_pk_fma_f32 v[12:13], v[82:83], v[116:117], v[12:13] op_sel_hi:[1,0,1]
	v_pk_fma_f32 v[10:11], v[80:81], v[116:117], v[10:11] op_sel_hi:[1,0,1]
	v_pk_fma_f32 v[4:5], v[82:83], v[118:119], v[4:5] op_sel_hi:[1,0,1]
	v_pk_fma_f32 v[2:3], v[80:81], v[118:119], v[2:3] op_sel_hi:[1,0,1]
	s_lshl_b32 s4, s4, 3
	s_or_b32 s4, s4, s25
	s_mul_hi_i32 s5, s4, 0x24000
	s_mul_i32 s4, s4, 0x24000
	s_add_u32 s4, s23, s4
	s_addc_u32 s5, s24, s5
	s_add_u32 s4, s4, s6
	s_addc_u32 s5, s5, s7
	v_lshl_add_u64 v[22:23], s[4:5], 0, v[16:17]
	global_store_dwordx4 v16, v[6:9], s[4:5]
	s_nop 1
	v_add_co_u32_e32 v6, vcc, 0xc000, v22
	s_nop 1
	v_addc_co_u32_e32 v7, vcc, 0, v23, vcc
	global_store_dwordx4 v[6:7], v[10:13], off
	v_add_co_u32_e32 v6, vcc, 0x18000, v22
	s_nop 1
	v_addc_co_u32_e32 v7, vcc, 0, v23, vcc
	global_store_dwordx4 v[6:7], v[2:5], off
	s_waitcnt lgkmcnt(0)
	s_branch .LBB0_18
